# GEMM1 epilogue scale loads (EpiZI8 pre) issued at the unit head instead of under the last MFMA block; epilogue wait vmcnt(0)->vmcnt(8) so the next tile's prefetch DMAs stay in flight
# baseline (speedup 1.0000x reference)
;     __device__ bool next(int i, Unit& u) const { const bool ok = StaticOrder::next(i >> 2, u); u.sub = i & 3; return ok; }
;     __device__ __forceinline__ void pre(Pre& p, const Unit& u, int wr, int wc, int lane) const {
;         const int fr = lane & 15, fq = lane >> 4, row0 = u.pm * BM + wr * 64 + fr, col0 = u.pn * BM + wc * 32 + 8 * fq;
; #pragma unroll
;         for (int bj = 0; bj < 2; ++bj)
; #pragma unroll
;             for (int n = 0; n < 2; ++n) p.wv[bj][n] = *(const f32x4*)(SW + col0 + bj * HALF + 4 * n);
; #pragma unroll
;         for (int i = 0; i < 8; ++i) p.rs[i] = SH[row0 + (i >> 2) * HALF + (i & 3) * 16];
;     }
; template <class Epi, class Sched, class Gemm, bool ALIGN_EPI = false, bool SP2 = false>
; __device__ __forceinline__ void gemm_phase(PG8_LAS unsigned char* lds, const Gemm g, const Sched& S, const Epi& E) {
;     ...
;         const bool has_next = S.next(ui + 1, nxt);
;         const char* nA = has_next ? (const char*)g.A + (size_t)nxt.pm * tstepA + (size_t)nxt.sub * g.a_sub : cA; const char* nB = has_next ? (const char*)g.Bt + (size_t)nxt.pn * tstepB + (size_t)nxt.sub * g.b_sub : cB;
;         for (int t = 0; t < nt; t += 2) {
;             const bool last = (t == nt - 2);
;             const char* a1 = cA + (size_t)(t + 1) * kstep;
;             const char* a2 = last ? nA : cA + (size_t)(t + 2) * kstep; const char* b2 = last ? nB : cB + (size_t)(t + 2) * kstep;
;             const char* a3 = a2 + kstep; const char* b3 = b2 + kstep;
.LBB0_134:
	s_ashr_i32 s43, s42, 31
	s_lshl_b64 s[44:45], s[42:43], 18
	s_add_u32 s44, s60, s44
	s_addc_u32 s45, s61, s45
	s_and_b64 s[46:47], s[4:5], exec
	s_cselect_b32 s7, s45, s3
	s_cselect_b32 s43, s44, s2
	s_ashr_i32 s41, s40, 31
	s_lshl_b64 s[46:47], s[40:41], 18
	s_add_u32 s46, s62, s46
	s_addc_u32 s47, s63, s47
	s_and_b64 s[50:51], s[4:5], exec
	s_cselect_b32 s79, s47, s49
	s_cselect_b32 s80, s46, s48
	s_lshl_b32 s33, s0, 8
	s_lshl_b32 s41, s6, 8
	v_or_b32_e32 v18, s41, v252
	v_or_b32_e32 v20, s70, v1
	s_add_u32 s81, s48, 0x100
	v_ashrrev_i32_e32 v19, 31, v18
	v_add_u32_e32 v20, s33, v20
	s_addc_u32 s82, s49, 0
	v_ashrrev_i32_e32 v21, 31, v20
	v_lshl_add_u64 v[238:239], v[18:19], 2, s[34:35]
	s_add_u32 s48, s2, 0x20080
	v_mov_b32_e32 v18, 0
	v_lshl_add_u64 v[240:241], v[20:21], 2, s[30:31]
	global_load_dwordx4 v[2:5], v[238:239], off offset:16
	global_load_dwordx4 v[6:9], v[238:239], off
	global_load_dwordx4 v[10:13], v[238:239], off offset:528
	global_load_dwordx4 v[14:17], v[238:239], off offset:512
	global_load_dword v226, v[240:241], off
	global_load_dword v228, v[240:241], off offset:64
	global_load_dword v230, v[240:241], off offset:128
	global_load_dword v232, v[240:241], off offset:192
	global_load_dword v234, v[240:241], off offset:512
	global_load_dword v235, v[240:241], off offset:576
	global_load_dword v236, v[240:241], off offset:640
	global_load_dword v237, v[240:241], off offset:704
	s_addc_u32 s49, s3, 0
	s_mov_b32 s2, -2
	v_mov_b32_e32 v19, v18
	v_mov_b32_e32 v20, v18
	v_mov_b32_e32 v21, v18
	v_mov_b32_e32 v22, v18
	v_mov_b32_e32 v23, v18
	v_mov_b32_e32 v24, v18
	v_mov_b32_e32 v25, v18
	v_mov_b32_e32 v34, v18
	v_mov_b32_e32 v35, v18
	v_mov_b32_e32 v36, v18
	v_mov_b32_e32 v37, v18
	v_mov_b32_e32 v38, v18
	v_mov_b32_e32 v39, v18
	v_mov_b32_e32 v40, v18
	v_mov_b32_e32 v41, v18
	v_mov_b32_e32 v50, v18
	v_mov_b32_e32 v51, v18
	v_mov_b32_e32 v52, v18
	v_mov_b32_e32 v53, v18
	v_mov_b32_e32 v54, v18
	v_mov_b32_e32 v55, v18
	v_mov_b32_e32 v56, v18
	v_mov_b32_e32 v57, v18
	v_mov_b32_e32 v66, v18
	v_mov_b32_e32 v67, v18
	v_mov_b32_e32 v68, v18
	v_mov_b32_e32 v69, v18
	v_mov_b32_e32 v70, v18
	v_mov_b32_e32 v71, v18
	v_mov_b32_e32 v72, v18
	v_mov_b32_e32 v73, v18
	v_mov_b32_e32 v26, v18
	v_mov_b32_e32 v27, v18
	v_mov_b32_e32 v28, v18
	v_mov_b32_e32 v29, v18
	v_mov_b32_e32 v30, v18
	v_mov_b32_e32 v31, v18
	v_mov_b32_e32 v32, v18
	v_mov_b32_e32 v33, v18
	v_mov_b32_e32 v42, v18
	v_mov_b32_e32 v43, v18
	v_mov_b32_e32 v44, v18
	v_mov_b32_e32 v45, v18
	v_mov_b32_e32 v46, v18
	v_mov_b32_e32 v47, v18
	v_mov_b32_e32 v48, v18
	v_mov_b32_e32 v49, v18
	v_mov_b32_e32 v58, v18
	v_mov_b32_e32 v59, v18
	v_mov_b32_e32 v60, v18
	v_mov_b32_e32 v61, v18
	v_mov_b32_e32 v62, v18
	v_mov_b32_e32 v63, v18
	v_mov_b32_e32 v64, v18
	v_mov_b32_e32 v65, v18
	v_mov_b32_e32 v74, v18
	v_mov_b32_e32 v75, v18
	v_mov_b32_e32 v76, v18
	v_mov_b32_e32 v77, v18
	v_mov_b32_e32 v78, v18
	v_mov_b32_e32 v79, v18
	v_mov_b32_e32 v80, v18
	v_mov_b32_e32 v81, v18
	v_mov_b32_e32 v82, v18
	v_mov_b32_e32 v83, v18
	v_mov_b32_e32 v84, v18
	v_mov_b32_e32 v85, v18
	v_mov_b32_e32 v86, v18
	v_mov_b32_e32 v87, v18
	v_mov_b32_e32 v88, v18
	v_mov_b32_e32 v89, v18
	v_mov_b32_e32 v98, v18
	v_mov_b32_e32 v99, v18
	v_mov_b32_e32 v100, v18
	v_mov_b32_e32 v101, v18
	v_mov_b32_e32 v102, v18
	v_mov_b32_e32 v103, v18
	v_mov_b32_e32 v104, v18
	v_mov_b32_e32 v105, v18
	v_mov_b32_e32 v114, v18
	v_mov_b32_e32 v115, v18
	v_mov_b32_e32 v116, v18
	v_mov_b32_e32 v117, v18
	v_mov_b32_e32 v118, v18
	v_mov_b32_e32 v119, v18
	v_mov_b32_e32 v120, v18
	v_mov_b32_e32 v121, v18
	v_mov_b32_e32 v130, v18
	v_mov_b32_e32 v131, v18
	v_mov_b32_e32 v132, v18
	v_mov_b32_e32 v133, v18
	v_mov_b32_e32 v134, v18
	v_mov_b32_e32 v135, v18
	v_mov_b32_e32 v136, v18
	v_mov_b32_e32 v137, v18
	v_mov_b32_e32 v90, v18
	v_mov_b32_e32 v91, v18
	v_mov_b32_e32 v92, v18
	v_mov_b32_e32 v93, v18
	v_mov_b32_e32 v94, v18
	v_mov_b32_e32 v95, v18
	v_mov_b32_e32 v96, v18
	v_mov_b32_e32 v97, v18
	v_mov_b32_e32 v106, v18
	v_mov_b32_e32 v107, v18
	v_mov_b32_e32 v108, v18
	v_mov_b32_e32 v109, v18
	v_mov_b32_e32 v110, v18
	v_mov_b32_e32 v111, v18
	v_mov_b32_e32 v112, v18
	v_mov_b32_e32 v113, v18
	v_mov_b32_e32 v122, v18
	v_mov_b32_e32 v123, v18
	v_mov_b32_e32 v124, v18
	v_mov_b32_e32 v125, v18
	v_mov_b32_e32 v126, v18
	v_mov_b32_e32 v127, v18
	v_mov_b32_e32 v128, v18
	v_mov_b32_e32 v129, v18
	v_mov_b32_e32 v138, v18
	v_mov_b32_e32 v139, v18
	v_mov_b32_e32 v140, v18
	v_mov_b32_e32 v141, v18
	v_mov_b32_e32 v142, v18
	v_mov_b32_e32 v143, v18
	v_mov_b32_e32 v144, v18
	v_mov_b32_e32 v145, v18
	s_branch .LBB0_136

; #define PG8_STAGE(bufoff, gbase, voff) do { _Pragma("unroll") for (int _i = 0; _i < 2; ++_i) \
;         __builtin_amdgcn_global_load_lds((const unsigned*)((const char*)(gbase) + (voff)[_i]), (PG8_LAS unsigned*)(lds + (bufoff) + ldsw + _i * 8192), 16, 0, 0); } while (0)
; #define PG8_LDA(dst, b, h) do { _Pragma("unroll") for (int m = 0; m < 4; ++m) _Pragma("unroll") for (int k = 0; k < 2; ++k) dst[m][k] = *(const PG8_LAS bf16x8*)(lds + PG8_SA(b, h) + aoff + m * 2048 + k * 1024); } while (0)
; #define PG8_LDB(dst, b, h) do { _Pragma("unroll") for (int n = 0; n < 2; ++n) _Pragma("unroll") for (int k = 0; k < 2; ++k) dst[n][k] = *(const PG8_LAS bf16x8*)(lds + PG8_SB(b, h) + boff + n * 2048 + k * 1024); } while (0)
; #define PG8_WAIT_V(n) asm volatile("s_waitcnt vmcnt(" #n ")" ::: "memory")
; #define PG8_WAIT_L(n) asm volatile("s_waitcnt lgkmcnt(" #n ")" ::: "memory")
; #define PG8_BAR __builtin_amdgcn_s_barrier()
; #define PG8_SCHED __builtin_amdgcn_sched_barrier(0)
; template <class Epi, class Sched, class Gemm, bool ALIGN_EPI = false, bool SP2 = false>
; __device__ __forceinline__ void gemm_phase(PG8_LAS unsigned char* lds, const Gemm g, const Sched& S, const Epi& E) {
;     ...
;         for (int t = 0; t < nt; t += 2) {
;             const bool last = (t == nt - 2);
;             const char* a1 = cA + (size_t)(t + 1) * kstep;
;             const char* a2 = last ? nA : cA + (size_t)(t + 2) * kstep; const char* b2 = last ? nB : cB + (size_t)(t + 2) * kstep;
;             const char* a3 = a2 + kstep; const char* b3 = b2 + kstep;
;             if (last && has_next) S.a_ready(nxt);
;             if constexpr (SP2) {
;             PG8_LDB(B0, 0, 0); PG8_LDB(B1, 0, 1); PG8_SCHED; PG8_LDA(At, 0, 0); PG8_STAGE(PG8_SA(1, 1), a1 + hstepA, voffA);
;             PG8_WAIT_V(8); PG8_WAIT_L(0); PG8_BAR; PG8_MMA(0, 0, At, B0); PG8_MMA(0, 1, At, B1); PG8_BAR; PG8_SCHED;
;             PG8_LDA(At, 0, 1); PG8_STAGE(PG8_SB(0, 0), b2, voffB); PG8_STAGE(PG8_SB(0, 1), b2 + hB1, voffB1); PG8_STAGE(PG8_SA(0, 0), a2, voffA);
;             PG8_WAIT_V(8); PG8_WAIT_L(0); PG8_BAR; PG8_MMA(1, 0, At, B0); PG8_MMA(1, 1, At, B1); PG8_BAR; PG8_SCHED;
;             PG8_LDB(B0, 1, 0); PG8_LDB(B1, 1, 1); PG8_SCHED; PG8_LDA(At, 1, 0); PG8_STAGE(PG8_SA(0, 1), a2 + hstepA, voffA);
.LBB0_136:
	s_add_u32 s0, s48, 0xfffe0080
	s_addc_u32 s1, s49, -1
	s_cmp_eq_u32 s2, 4
	s_cselect_b32 s53, s7, s1
	s_cselect_b32 s52, s43, s0
	s_cselect_b32 s55, s79, s82
	s_cselect_b32 s54, s80, s81
	s_add_i32 s95, s76, s64
	ds_read_b128 v[174:177], v253
	ds_read_b128 v[170:173], v253 offset:1024
	ds_read_b128 v[166:169], v253 offset:2048
	ds_read_b128 v[162:165], v253 offset:3072
	ds_read_b128 v[158:161], v254
	ds_read_b128 v[154:157], v254 offset:1024
	ds_read_b128 v[150:153], v254 offset:2048
	ds_read_b128 v[146:149], v254 offset:3072
	s_add_i32 m0, s65, 0xc000
	s_add_i32 s96, s65, 0xe000
	s_add_i32 s92, s95, 0x2000
	s_add_u32 s56, s54, 0x20000
	s_addc_u32 s57, s55, 0
	s_add_i32 s94, s77, s64
	s_add_i32 s93, s94, 0x2000
	s_add_i32 s91, 0, 0x18000
	s_add_i32 s90, 0, 0x1c000
	s_add_u32 s50, s52, 0x20000
	s_addc_u32 s51, s53, 0
	s_add_i32 s83, s91, s64
	s_add_i32 s3, s83, 0x2000
	s_add_u32 s0, s54, 0x20080
	s_addc_u32 s1, s55, 0
	s_add_i32 s89, s90, s64
	s_add_i32 s88, s89, 0x2000
	s_cmp_lg_u32 s2, 4
	v_lshl_add_u64 v[242:243], s[48:49], 0, v[220:221]
	ds_read_b128 v[190:193], v222
	ds_read_b128 v[194:197], v222 offset:1024
	ds_read_b128 v[198:201], v222 offset:2048
	ds_read_b128 v[202:205], v222 offset:3072
	ds_read_b128 v[206:209], v222 offset:4096
	ds_read_b128 v[186:189], v222 offset:5120
	ds_read_b128 v[182:185], v222 offset:6144
	ds_read_b128 v[178:181], v222 offset:7168
	global_load_lds_dwordx4 v[242:243], off
	v_lshl_add_u64 v[242:243], s[48:49], 0, v[218:219]
	s_mov_b32 m0, s96
	s_nop 0
	global_load_lds_dwordx4 v[242:243], off
	s_waitcnt vmcnt(8)
	s_waitcnt lgkmcnt(0)
	s_barrier
	s_setprio 1
	s_waitcnt lgkmcnt(0)
	v_mfma_i32_16x16x64_i8 v[142:145], v[174:177], v[190:193], v[142:145]
	v_mfma_i32_16x16x64_i8 v[138:141], v[166:169], v[190:193], v[138:141]
	v_mfma_i32_16x16x64_i8 v[126:129], v[174:177], v[198:201], v[126:129]
	v_mfma_i32_16x16x64_i8 v[122:125], v[166:169], v[198:201], v[122:125]
	v_mfma_i32_16x16x64_i8 v[110:113], v[174:177], v[206:209], v[110:113]
	v_mfma_i32_16x16x64_i8 v[106:109], v[166:169], v[206:209], v[106:109]
	v_mfma_i32_16x16x64_i8 v[94:97], v[174:177], v[182:185], v[94:97]
	v_mfma_i32_16x16x64_i8 v[90:93], v[166:169], v[182:185], v[90:93]
	v_mfma_i32_16x16x64_i8 v[142:145], v[170:173], v[194:197], v[142:145]
	v_mfma_i32_16x16x64_i8 v[138:141], v[162:165], v[194:197], v[138:141]
	v_mfma_i32_16x16x64_i8 v[126:129], v[170:173], v[202:205], v[126:129]
	v_mfma_i32_16x16x64_i8 v[122:125], v[162:165], v[202:205], v[122:125]
	v_mfma_i32_16x16x64_i8 v[110:113], v[170:173], v[186:189], v[110:113]
	v_mfma_i32_16x16x64_i8 v[106:109], v[162:165], v[186:189], v[106:109]
	v_mfma_i32_16x16x64_i8 v[94:97], v[170:173], v[178:181], v[94:97]
	v_mfma_i32_16x16x64_i8 v[90:93], v[162:165], v[178:181], v[90:93]
	s_setprio 0
	s_setprio 1
	v_mfma_i32_16x16x64_i8 v[134:137], v[158:161], v[190:193], v[134:137]
	v_mfma_i32_16x16x64_i8 v[130:133], v[150:153], v[190:193], v[130:133]
	v_mfma_i32_16x16x64_i8 v[118:121], v[158:161], v[198:201], v[118:121]
	v_mfma_i32_16x16x64_i8 v[114:117], v[150:153], v[198:201], v[114:117]
	v_mfma_i32_16x16x64_i8 v[102:105], v[158:161], v[206:209], v[102:105]
	v_mfma_i32_16x16x64_i8 v[98:101], v[150:153], v[206:209], v[98:101]
	v_mfma_i32_16x16x64_i8 v[86:89], v[158:161], v[182:185], v[86:89]
	v_mfma_i32_16x16x64_i8 v[82:85], v[150:153], v[182:185], v[82:85]
	v_mfma_i32_16x16x64_i8 v[134:137], v[154:157], v[194:197], v[134:137]
	v_mfma_i32_16x16x64_i8 v[130:133], v[146:149], v[194:197], v[130:133]
	v_mfma_i32_16x16x64_i8 v[118:121], v[154:157], v[202:205], v[118:121]
	v_mfma_i32_16x16x64_i8 v[114:117], v[146:149], v[202:205], v[114:117]
	v_mfma_i32_16x16x64_i8 v[102:105], v[154:157], v[186:189], v[102:105]
	v_mfma_i32_16x16x64_i8 v[98:101], v[146:149], v[186:189], v[98:101]
	v_mfma_i32_16x16x64_i8 v[86:89], v[154:157], v[178:181], v[86:89]
	v_mfma_i32_16x16x64_i8 v[82:85], v[146:149], v[178:181], v[82:85]
	s_setprio 0
	s_barrier
	s_mov_b32 m0, s95
	v_lshl_add_u64 v[242:243], s[54:55], 0, v[212:213]
	ds_read_b128 v[190:193], v222 offset:16384
	ds_read_b128 v[194:197], v222 offset:17408
	ds_read_b128 v[198:201], v222 offset:18432
	ds_read_b128 v[202:205], v222 offset:19456
	ds_read_b128 v[206:209], v222 offset:20480
	ds_read_b128 v[186:189], v222 offset:21504
	ds_read_b128 v[182:185], v222 offset:22528
	ds_read_b128 v[178:181], v222 offset:23552
	global_load_lds_dwordx4 v[242:243], off
	v_lshl_add_u64 v[244:245], s[54:55], 0, v[216:217]
	s_mov_b32 m0, s92
	v_lshl_add_u64 v[246:247], s[56:57], 0, v[212:213]
	global_load_lds_dwordx4 v[244:245], off
	s_mov_b32 m0, s94
	v_lshl_add_u64 v[248:249], s[52:53], 0, v[214:215]
	global_load_lds_dwordx4 v[246:247], off
	v_lshl_add_u64 v[246:247], s[56:57], 0, v[216:217]
	s_mov_b32 m0, s93
	s_nop 0
	global_load_lds_dwordx4 v[246:247], off
	v_lshl_add_u64 v[246:247], s[52:53], 0, v[210:211]
	s_mov_b32 m0, s65
	s_nop 0
	global_load_lds_dwordx4 v[246:247], off
	s_mov_b32 m0, s66
	s_nop 0
	global_load_lds_dwordx4 v[248:249], off
	s_waitcnt vmcnt(8)
	s_waitcnt lgkmcnt(0)
	s_barrier
; #define PG8_STAGE(bufoff, gbase, voff) do { _Pragma("unroll") for (int _i = 0; _i < 2; ++_i) \
;         __builtin_amdgcn_global_load_lds((const unsigned*)((const char*)(gbase) + (voff)[_i]), (PG8_LAS unsigned*)(lds + (bufoff) + ldsw + _i * 8192), 16, 0, 0); } while (0)
; #define PG8_LDA(dst, b, h) do { _Pragma("unroll") for (int m = 0; m < 4; ++m) _Pragma("unroll") for (int k = 0; k < 2; ++k) dst[m][k] = *(const PG8_LAS bf16x8*)(lds + PG8_SA(b, h) + aoff + m * 2048 + k * 1024); } while (0)
; #define PG8_LDB(dst, b, h) do { _Pragma("unroll") for (int n = 0; n < 2; ++n) _Pragma("unroll") for (int k = 0; k < 2; ++k) dst[n][k] = *(const PG8_LAS bf16x8*)(lds + PG8_SB(b, h) + boff + n * 2048 + k * 1024); } while (0)
; #define PG8_MMA(ai, bj, At, Bt) do { __builtin_amdgcn_s_setprio(1); _Pragma("unroll") for (int m = 0; m < 4; ++m) _Pragma("unroll") for (int n = 0; n < 2; ++n) _Pragma("unroll") for (int k = 0; k < 2; ++k) \
;         acc[ai][bj][m][n] = Gemm::i8 ? ::mfma16i8_g(Bt[n][k], At[m][k], acc[ai][bj][m][n]) : ::mfma16_g(Bt[n][k], At[m][k], acc[ai][bj][m][n]); __builtin_amdgcn_s_setprio(0); } while (0)
; #define PG8_WAIT_V(n) asm volatile("s_waitcnt vmcnt(" #n ")" ::: "memory")
; #define PG8_WAIT_L(n) asm volatile("s_waitcnt lgkmcnt(" #n ")" ::: "memory")
; #define PG8_BAR __builtin_amdgcn_s_barrier()
; #define PG8_SCHED __builtin_amdgcn_sched_barrier(0)
; template <class Epi, class Sched, class Gemm, bool ALIGN_EPI = false, bool SP2 = false>
; __device__ __forceinline__ void gemm_phase(PG8_LAS unsigned char* lds, const Gemm g, const Sched& S, const Epi& E) {
;     ...
;             PG8_WAIT_V(8); PG8_WAIT_L(0); PG8_BAR; PG8_MMA(1, 0, At, B0); PG8_MMA(1, 1, At, B1); PG8_BAR; PG8_SCHED;
;             PG8_LDB(B0, 1, 0); PG8_LDB(B1, 1, 1); PG8_SCHED; PG8_LDA(At, 1, 0); PG8_STAGE(PG8_SA(0, 1), a2 + hstepA, voffA);
;             PG8_WAIT_V(8); PG8_WAIT_L(0); PG8_BAR; PG8_MMA(0, 0, At, B0); PG8_MMA(0, 1, At, B1); PG8_BAR; PG8_SCHED;
;             PG8_LDA(At, 1, 1); PG8_STAGE(PG8_SB(1, 0), b3, voffB); PG8_STAGE(PG8_SB(1, 1), b3 + hB1, voffB1); PG8_STAGE(PG8_SA(1, 0), a3, voffA);
;             PG8_WAIT_V(8);
;             if constexpr (epi_pre<Epi>::value) { if (last) E.pre(pre, cur, wr, wc, lane); }
;             PG8_WAIT_L(0); PG8_BAR; PG8_MMA(1, 0, At, B0); PG8_MMA(1, 1, At, B1); PG8_BAR; PG8_SCHED;
	s_setprio 1
	s_waitcnt lgkmcnt(0)
	v_mfma_i32_16x16x64_i8 v[78:81], v[174:177], v[190:193], v[78:81]
	v_mfma_i32_16x16x64_i8 v[74:77], v[166:169], v[190:193], v[74:77]
	v_mfma_i32_16x16x64_i8 v[62:65], v[174:177], v[198:201], v[62:65]
	v_mfma_i32_16x16x64_i8 v[58:61], v[166:169], v[198:201], v[58:61]
	v_mfma_i32_16x16x64_i8 v[46:49], v[174:177], v[206:209], v[46:49]
	v_mfma_i32_16x16x64_i8 v[42:45], v[166:169], v[206:209], v[42:45]
	v_mfma_i32_16x16x64_i8 v[30:33], v[174:177], v[182:185], v[30:33]
	v_mfma_i32_16x16x64_i8 v[26:29], v[166:169], v[182:185], v[26:29]
	v_mfma_i32_16x16x64_i8 v[78:81], v[170:173], v[194:197], v[78:81]
	v_mfma_i32_16x16x64_i8 v[74:77], v[162:165], v[194:197], v[74:77]
	v_mfma_i32_16x16x64_i8 v[62:65], v[170:173], v[202:205], v[62:65]
	v_mfma_i32_16x16x64_i8 v[58:61], v[162:165], v[202:205], v[58:61]
	v_mfma_i32_16x16x64_i8 v[46:49], v[170:173], v[186:189], v[46:49]
	v_mfma_i32_16x16x64_i8 v[42:45], v[162:165], v[186:189], v[42:45]
	v_mfma_i32_16x16x64_i8 v[30:33], v[170:173], v[178:181], v[30:33]
	v_mfma_i32_16x16x64_i8 v[26:29], v[162:165], v[178:181], v[26:29]
	s_setprio 0
	s_setprio 1
	v_mfma_i32_16x16x64_i8 v[70:73], v[158:161], v[190:193], v[70:73]
	v_mfma_i32_16x16x64_i8 v[66:69], v[150:153], v[190:193], v[66:69]
	v_mfma_i32_16x16x64_i8 v[54:57], v[158:161], v[198:201], v[54:57]
	v_mfma_i32_16x16x64_i8 v[50:53], v[150:153], v[198:201], v[50:53]
	v_mfma_i32_16x16x64_i8 v[38:41], v[158:161], v[206:209], v[38:41]
	v_mfma_i32_16x16x64_i8 v[34:37], v[150:153], v[206:209], v[34:37]
	v_mfma_i32_16x16x64_i8 v[22:25], v[158:161], v[182:185], v[22:25]
	v_mfma_i32_16x16x64_i8 v[18:21], v[150:153], v[182:185], v[18:21]
	v_mfma_i32_16x16x64_i8 v[70:73], v[154:157], v[194:197], v[70:73]
	v_mfma_i32_16x16x64_i8 v[66:69], v[146:149], v[194:197], v[66:69]
	v_mfma_i32_16x16x64_i8 v[54:57], v[154:157], v[202:205], v[54:57]
	v_mfma_i32_16x16x64_i8 v[50:53], v[146:149], v[202:205], v[50:53]
	v_mfma_i32_16x16x64_i8 v[38:41], v[154:157], v[186:189], v[38:41]
	v_mfma_i32_16x16x64_i8 v[34:37], v[146:149], v[186:189], v[34:37]
	v_mfma_i32_16x16x64_i8 v[22:25], v[154:157], v[178:181], v[22:25]
	v_mfma_i32_16x16x64_i8 v[18:21], v[146:149], v[178:181], v[18:21]
	s_setprio 0
	s_barrier
	v_add_u32_e32 v146, s91, v251
	ds_read_b128 v[174:177], v146
	ds_read_b128 v[170:173], v146 offset:1024
	ds_read_b128 v[166:169], v146 offset:2048
	ds_read_b128 v[162:165], v146 offset:3072
	v_add_u32_e32 v146, s90, v251
	ds_read_b128 v[150:153], v146
	ds_read_b128 v[154:157], v146 offset:1024
	ds_read_b128 v[158:161], v146 offset:2048
	ds_read_b128 v[146:149], v146 offset:3072
	s_mov_b32 m0, s67
	v_lshl_add_u64 v[224:225], s[50:51], 0, v[210:211]
	ds_read_b128 v[190:193], v222 offset:32768
	ds_read_b128 v[194:197], v222 offset:33792
	ds_read_b128 v[198:201], v222 offset:34816
	ds_read_b128 v[202:205], v222 offset:35840
	ds_read_b128 v[206:209], v222 offset:36864
	ds_read_b128 v[186:189], v222 offset:37888
	ds_read_b128 v[182:185], v222 offset:38912
	ds_read_b128 v[178:181], v222 offset:39936
	global_load_lds_dwordx4 v[224:225], off
	v_lshl_add_u64 v[224:225], s[50:51], 0, v[214:215]
	s_mov_b32 m0, s68
	s_nop 0
	global_load_lds_dwordx4 v[224:225], off
	s_waitcnt vmcnt(8)
	s_waitcnt lgkmcnt(0)
	s_barrier
	s_setprio 1
	s_waitcnt lgkmcnt(0)
	v_mfma_i32_16x16x64_i8 v[142:145], v[174:177], v[190:193], v[142:145]
	v_mfma_i32_16x16x64_i8 v[138:141], v[166:169], v[190:193], v[138:141]
	v_mfma_i32_16x16x64_i8 v[126:129], v[174:177], v[198:201], v[126:129]
	v_mfma_i32_16x16x64_i8 v[122:125], v[166:169], v[198:201], v[122:125]
	v_mfma_i32_16x16x64_i8 v[110:113], v[174:177], v[206:209], v[110:113]
	v_mfma_i32_16x16x64_i8 v[106:109], v[166:169], v[206:209], v[106:109]
	v_mfma_i32_16x16x64_i8 v[94:97], v[174:177], v[182:185], v[94:97]
	v_mfma_i32_16x16x64_i8 v[90:93], v[166:169], v[182:185], v[90:93]
	v_mfma_i32_16x16x64_i8 v[142:145], v[170:173], v[194:197], v[142:145]
	v_mfma_i32_16x16x64_i8 v[138:141], v[162:165], v[194:197], v[138:141]
	v_mfma_i32_16x16x64_i8 v[126:129], v[170:173], v[202:205], v[126:129]
	v_mfma_i32_16x16x64_i8 v[122:125], v[162:165], v[202:205], v[122:125]
	v_mfma_i32_16x16x64_i8 v[110:113], v[170:173], v[186:189], v[110:113]
	v_mfma_i32_16x16x64_i8 v[106:109], v[162:165], v[186:189], v[106:109]
	v_mfma_i32_16x16x64_i8 v[94:97], v[170:173], v[178:181], v[94:97]
	v_mfma_i32_16x16x64_i8 v[90:93], v[162:165], v[178:181], v[90:93]
	s_setprio 0
	s_setprio 1
	v_mfma_i32_16x16x64_i8 v[134:137], v[150:153], v[190:193], v[134:137]
	v_mfma_i32_16x16x64_i8 v[130:133], v[158:161], v[190:193], v[130:133]
	v_mfma_i32_16x16x64_i8 v[118:121], v[150:153], v[198:201], v[118:121]
	v_mfma_i32_16x16x64_i8 v[114:117], v[158:161], v[198:201], v[114:117]
	v_mfma_i32_16x16x64_i8 v[102:105], v[150:153], v[206:209], v[102:105]
	v_mfma_i32_16x16x64_i8 v[98:101], v[158:161], v[206:209], v[98:101]
	v_mfma_i32_16x16x64_i8 v[86:89], v[150:153], v[182:185], v[86:89]
	v_mfma_i32_16x16x64_i8 v[82:85], v[158:161], v[182:185], v[82:85]
	v_mfma_i32_16x16x64_i8 v[134:137], v[154:157], v[194:197], v[134:137]
	v_mfma_i32_16x16x64_i8 v[130:133], v[146:149], v[194:197], v[130:133]
	v_mfma_i32_16x16x64_i8 v[118:121], v[154:157], v[202:205], v[118:121]
	v_mfma_i32_16x16x64_i8 v[114:117], v[146:149], v[202:205], v[114:117]
	v_mfma_i32_16x16x64_i8 v[102:105], v[154:157], v[186:189], v[102:105]
	v_mfma_i32_16x16x64_i8 v[98:101], v[146:149], v[186:189], v[98:101]
	v_mfma_i32_16x16x64_i8 v[86:89], v[154:157], v[178:181], v[86:89]
	v_mfma_i32_16x16x64_i8 v[82:85], v[146:149], v[178:181], v[82:85]
	s_setprio 0
	s_barrier
	s_mov_b32 m0, s83
	v_lshl_add_u64 v[224:225], v[242:243], 0, s[36:37]
	ds_read_b128 v[206:209], v222 offset:49152
	ds_read_b128 v[202:205], v222 offset:50176
	ds_read_b128 v[194:197], v222 offset:51200
	ds_read_b128 v[198:201], v222 offset:52224
	ds_read_b128 v[186:189], v222 offset:53248
	ds_read_b128 v[190:193], v222 offset:54272
	ds_read_b128 v[182:185], v222 offset:55296
	ds_read_b128 v[178:181], v222 offset:56320
	global_load_lds_dwordx4 v[224:225], off
	v_lshl_add_u64 v[224:225], v[244:245], 0, s[36:37]
	s_mov_b32 m0, s3
	s_nop 0
	global_load_lds_dwordx4 v[224:225], off
	v_lshl_add_u64 v[224:225], s[0:1], 0, v[212:213]
	s_mov_b32 m0, s89
	s_nop 0
	global_load_lds_dwordx4 v[224:225], off
	v_lshl_add_u64 v[224:225], s[0:1], 0, v[216:217]
	s_mov_b32 m0, s88
	s_nop 0
	global_load_lds_dwordx4 v[224:225], off
	v_lshl_add_u64 v[224:225], v[246:247], 0, s[36:37]
	s_mov_b32 m0, s72
	s_nop 0
	global_load_lds_dwordx4 v[224:225], off
	v_lshl_add_u64 v[224:225], v[248:249], 0, s[36:37]
	s_mov_b32 m0, s73
	s_nop 0
	global_load_lds_dwordx4 v[224:225], off
	s_waitcnt vmcnt(8)
	s_cbranch_scc1 .LBB0_135
	s_branch .LBB0_135

; __device__ __forceinline__ unsigned cvt_pk_bf16(float lo, float hi) { return ::pk2(lo, hi); }
;     __device__ __forceinline__ void operator()(const f32x4 (&acc)[2][2][4][2], const Pre& p, const Unit& u, int wr, int wc, int fr, int fq) const {
;         asm volatile("" : "+v"(fr), "+v"(fq));
;         const int row0 = u.pm * BM + wr * 64 + fr, col0 = u.pn * BM + wc * 32 + 8 * fq;
;         const bool glu = (u.pn * BM >= ZB) && (u.pn * BM < ZQ);
; #pragma unroll
;         for (int ai = 0; ai < 2; ++ai)
; #pragma unroll
;             for (int m = 0; m < 4; ++m) { bf16_t* rowp = O + (size_t)(row0 + ai * HALF + m * 16) * ldc;
;                 const float rs = p.rs[ai * 4 + m];
; #pragma unroll
;                 for (int bj = 0; bj < 2; ++bj) {
;                     const f32x4 v0 = (__builtin_convertvector(__builtin_bit_cast(i32x4, acc[ai][bj][m][0]), f32x4) * p.wv[bj][0]) * rs, v1 = (__builtin_convertvector(__builtin_bit_cast(i32x4, acc[ai][bj][m][1]), f32x4) * p.wv[bj][1]) * rs;
;                     if (glu) {
;                         const float o0 = v0[0] * __builtin_amdgcn_rcpf(1.f + __builtin_amdgcn_exp2f(v0[1] * -1.44269504f)), o1 = v0[2] * __builtin_amdgcn_rcpf(1.f + __builtin_amdgcn_exp2f(v0[3] * -1.44269504f));
;                         const float o2 = v1[0] * __builtin_amdgcn_rcpf(1.f + __builtin_amdgcn_exp2f(v1[1] * -1.44269504f)), o3 = v1[2] * __builtin_amdgcn_rcpf(1.f + __builtin_amdgcn_exp2f(v1[3] * -1.44269504f));
;                         u32x2 w; w.x = cvt_pk_bf16(o0, o1); w.y = cvt_pk_bf16(o2, o3);
;                         *(u32x2*)(rowp + ZB + ((col0 + bj * HALF - ZB) >> 1)) = w;
;                     } else {
;                         u32x4 w; w.x = cvt_pk_bf16(v0[0], v0[1]); w.y = cvt_pk_bf16(v0[2], v0[3]); w.z = cvt_pk_bf16(v1[0], v1[1]); w.w = cvt_pk_bf16(v1[2], v1[3]);
;                         *(u32x4*)(rowp + col0 + bj * HALF) = w; } } }
.LBB0_140:
	v_mov_b32_e32 v147, v1
	v_mov_b32_e32 v146, v250
	s_or_b32 s0, s41, s71
	v_lshl_add_u32 v146, v146, 3, s0
	s_add_i32 s0, s6, -1
	v_cvt_f32_i32_e32 v153, v145
	v_cvt_f32_i32_e32 v152, v144
	s_cmp_gt_u32 s0, 1
	s_cselect_b64 s[0:1], -1, 0
	s_add_i32 s33, s33, s70
	v_add_u32_e32 v154, s33, v147
	v_mov_b64_e32 v[148:149], s[28:29]
	v_cvt_f32_i32_e32 v151, v143
	v_cvt_f32_i32_e32 v150, v142
	v_mad_i64_i32 v[142:143], s[2:3], v154, s78, v[148:149]
	s_waitcnt vmcnt(8)
	v_pk_mul_f32 v[148:149], v[8:9], v[152:153]
	v_cvt_f32_i32_e32 v139, v139
	v_cvt_f32_i32_e32 v153, v141
	v_cvt_f32_i32_e32 v152, v140
	v_cvt_f32_i32_e32 v138, v138
	v_pk_mul_f32 v[150:151], v[6:7], v[150:151]
	v_ashrrev_i32_e32 v147, 31, v146
	v_pk_mul_f32 v[140:141], v[148:149], v[226:227] op_sel_hi:[1,0]
	v_pk_mul_f32 v[148:149], v[150:151], v[226:227] op_sel_hi:[1,0]
	v_pk_mul_f32 v[150:151], v[4:5], v[152:153]
	v_pk_mul_f32 v[138:139], v[2:3], v[138:139]
	v_lshl_add_u64 v[144:145], v[146:147], 1, v[142:143]
	v_pk_mul_f32 v[152:153], v[150:151], v[226:227] op_sel_hi:[1,0]
	v_pk_mul_f32 v[150:151], v[138:139], v[226:227] op_sel_hi:[1,0]
	s_mov_b64 s[2:3], -1
	s_and_b64 vcc, exec, s[0:1]
	v_readlane_b32 s88, v255, 5
	s_cbranch_vccz .LBB0_142
	v_cvt_pk_bf16_f32 v156, v148, v149
	v_cvt_pk_bf16_f32 v157, v140, v141
	v_cvt_pk_bf16_f32 v158, v150, v151
	v_cvt_pk_bf16_f32 v159, v152, v153
	global_store_dwordx4 v[144:145], v[156:159], off
	s_mov_b64 s[2:3], 0
